# GEMM K-loops with no s_setprio at all (loaders are VALU-free now), on top of merged waits
# baseline (speedup 1.0000x reference)
.LBB0_204:
	s_ashr_i32 s27, s26, 31
	s_lshl_b64 s[16:17], s[26:27], 20
	s_add_u32 s38, s0, s16
	s_addc_u32 s39, s1, s17
	s_and_b64 s[16:17], s[36:37], exec
	s_cselect_b32 s27, s39, s43
	s_cselect_b32 s73, s38, s42
	s_ashr_i32 s23, s22, 31
	s_lshl_b64 s[16:17], s[22:23], 20
	v_readlane_b32 s23, v255, 4
	s_add_u32 s40, s23, s16
	v_readlane_b32 s16, v255, 5
	s_addc_u32 s41, s16, s17
	s_and_b64 s[16:17], s[36:37], exec
	s_cselect_b32 s23, s41, s29
	s_cselect_b32 s74, s40, s28
	s_add_u32 s42, s42, 0x80080
	s_addc_u32 s43, s43, 0
	s_add_u32 s77, s28, 0x100
	v_mov_b32_e32 v4, 0
	s_addc_u32 s78, s29, 0
	s_mov_b32 s88, -2
	v_mov_b32_e32 v5, v4
	v_mov_b32_e32 v6, v4
	v_mov_b32_e32 v7, v4
	v_mov_b32_e32 v8, v4
	v_mov_b32_e32 v9, v4
	v_mov_b32_e32 v10, v4
	v_mov_b32_e32 v11, v4
	v_mov_b32_e32 v20, v4
	v_mov_b32_e32 v21, v4
	s_waitcnt lgkmcnt(0)
	v_mov_b32_e32 v22, v4
	v_mov_b32_e32 v23, v4
	v_mov_b32_e32 v24, v4
	v_mov_b32_e32 v25, v4
	v_mov_b32_e32 v26, v4
	v_mov_b32_e32 v27, v4
	v_mov_b32_e32 v36, v4
	v_mov_b32_e32 v37, v4
	v_mov_b32_e32 v38, v4
	v_mov_b32_e32 v39, v4
	v_mov_b32_e32 v40, v4
	v_mov_b32_e32 v41, v4
	v_mov_b32_e32 v42, v4
	v_mov_b32_e32 v43, v4
	v_mov_b32_e32 v52, v4
	v_mov_b32_e32 v53, v4
	v_mov_b32_e32 v54, v4
	v_mov_b32_e32 v55, v4
	v_mov_b32_e32 v56, v4
	v_mov_b32_e32 v57, v4
	v_mov_b32_e32 v58, v4
	v_mov_b32_e32 v59, v4
	v_mov_b32_e32 v12, v4
	v_mov_b32_e32 v13, v4
	v_mov_b32_e32 v14, v4
	v_mov_b32_e32 v15, v4
	v_mov_b32_e32 v16, v4
	v_mov_b32_e32 v17, v4
	v_mov_b32_e32 v18, v4
	v_mov_b32_e32 v19, v4
	v_mov_b32_e32 v28, v4
	v_mov_b32_e32 v29, v4
	v_mov_b32_e32 v30, v4
	v_mov_b32_e32 v31, v4
	v_mov_b32_e32 v32, v4
	v_mov_b32_e32 v33, v4
	v_mov_b32_e32 v34, v4
	v_mov_b32_e32 v35, v4
	v_mov_b32_e32 v44, v4
	v_mov_b32_e32 v45, v4
	v_mov_b32_e32 v46, v4
	v_mov_b32_e32 v47, v4
	v_mov_b32_e32 v48, v4
	v_mov_b32_e32 v49, v4
	v_mov_b32_e32 v50, v4
	v_mov_b32_e32 v51, v4
	v_mov_b32_e32 v60, v4
	v_mov_b32_e32 v61, v4
	v_mov_b32_e32 v62, v4
	v_mov_b32_e32 v63, v4
	v_mov_b32_e32 v64, v4
	v_mov_b32_e32 v65, v4
	v_mov_b32_e32 v66, v4
	v_mov_b32_e32 v67, v4
	v_mov_b32_e32 v68, v4
	v_mov_b32_e32 v69, v4
	v_mov_b32_e32 v70, v4
	v_mov_b32_e32 v71, v4
	v_mov_b32_e32 v72, v4
	v_mov_b32_e32 v73, v4
	v_mov_b32_e32 v74, v4
	v_mov_b32_e32 v75, v4
	v_mov_b32_e32 v84, v4
	v_mov_b32_e32 v85, v4
	v_mov_b32_e32 v86, v4
	v_mov_b32_e32 v87, v4
	v_mov_b32_e32 v88, v4
	v_mov_b32_e32 v89, v4
	v_mov_b32_e32 v90, v4
	v_mov_b32_e32 v91, v4
	v_mov_b32_e32 v100, v4
	v_mov_b32_e32 v101, v4
	v_mov_b32_e32 v102, v4
	v_mov_b32_e32 v103, v4
	v_mov_b32_e32 v104, v4
	v_mov_b32_e32 v105, v4
	v_mov_b32_e32 v106, v4
	v_mov_b32_e32 v107, v4
	v_mov_b32_e32 v116, v4
	v_mov_b32_e32 v117, v4
	v_mov_b32_e32 v118, v4
	v_mov_b32_e32 v119, v4
	v_mov_b32_e32 v120, v4
	v_mov_b32_e32 v121, v4
	v_mov_b32_e32 v122, v4
	v_mov_b32_e32 v123, v4
	v_mov_b32_e32 v76, v4
	v_mov_b32_e32 v77, v4
	v_mov_b32_e32 v78, v4
	v_mov_b32_e32 v79, v4
	v_mov_b32_e32 v80, v4
	v_mov_b32_e32 v81, v4
	v_mov_b32_e32 v82, v4
	v_mov_b32_e32 v83, v4
	v_mov_b32_e32 v92, v4
	v_mov_b32_e32 v93, v4
	v_mov_b32_e32 v94, v4
	v_mov_b32_e32 v95, v4
	v_mov_b32_e32 v96, v4
	v_mov_b32_e32 v97, v4
	v_mov_b32_e32 v98, v4
	v_mov_b32_e32 v99, v4
	v_mov_b32_e32 v108, v4
	v_mov_b32_e32 v109, v4
	v_mov_b32_e32 v110, v4
	v_mov_b32_e32 v111, v4
	v_mov_b32_e32 v112, v4
	v_mov_b32_e32 v113, v4
	v_mov_b32_e32 v114, v4
	v_mov_b32_e32 v115, v4
	v_mov_b32_e32 v124, v4
	v_mov_b32_e32 v125, v4
	v_mov_b32_e32 v126, v4
	v_mov_b32_e32 v127, v4
	v_mov_b32_e32 v128, v4
	v_mov_b32_e32 v129, v4
	v_mov_b32_e32 v130, v4
	v_mov_b32_e32 v131, v4
	v_readfirstlane_b32 s100, v0
	s_nop 0
	s_cmpk_ge_u32 s100, 0x100
	s_cbranch_scc0 .Lsp_205


.LBB0_365:
	s_add_u32 s31, s28, 0x100
	v_mov_b32_e32 v4, 0
	s_addc_u32 s33, s29, 0
	s_mov_b32 s22, -2
	v_mov_b32_e32 v5, v4
	v_mov_b32_e32 v6, v4
	v_mov_b32_e32 v7, v4
	v_mov_b32_e32 v8, v4
	v_mov_b32_e32 v9, v4
	v_mov_b32_e32 v10, v4
	v_mov_b32_e32 v11, v4
	v_mov_b32_e32 v20, v4
	v_mov_b32_e32 v21, v4
	v_mov_b32_e32 v22, v4
	v_mov_b32_e32 v23, v4
	v_mov_b32_e32 v24, v4
	v_mov_b32_e32 v25, v4
	s_waitcnt lgkmcnt(0)
	v_mov_b32_e32 v26, v4
	v_mov_b32_e32 v27, v4
	v_mov_b32_e32 v36, v4
	v_mov_b32_e32 v37, v4
	v_mov_b32_e32 v38, v4
	v_mov_b32_e32 v39, v4
	v_mov_b32_e32 v40, v4
	v_mov_b32_e32 v41, v4
	v_mov_b32_e32 v42, v4
	v_mov_b32_e32 v43, v4
	v_mov_b32_e32 v52, v4
	v_mov_b32_e32 v53, v4
	v_mov_b32_e32 v54, v4
	v_mov_b32_e32 v55, v4
	v_mov_b32_e32 v56, v4
	v_mov_b32_e32 v57, v4
	v_mov_b32_e32 v58, v4
	v_mov_b32_e32 v59, v4
	v_mov_b32_e32 v12, v4
	v_mov_b32_e32 v13, v4
	v_mov_b32_e32 v14, v4
	v_mov_b32_e32 v15, v4
	v_mov_b32_e32 v16, v4
	v_mov_b32_e32 v17, v4
	v_mov_b32_e32 v18, v4
	v_mov_b32_e32 v19, v4
	v_mov_b32_e32 v28, v4
	v_mov_b32_e32 v29, v4
	v_mov_b32_e32 v30, v4
	v_mov_b32_e32 v31, v4
	v_mov_b32_e32 v32, v4
	v_mov_b32_e32 v33, v4
	v_mov_b32_e32 v34, v4
	v_mov_b32_e32 v35, v4
	v_mov_b32_e32 v44, v4
	v_mov_b32_e32 v45, v4
	v_mov_b32_e32 v46, v4
	v_mov_b32_e32 v47, v4
	v_mov_b32_e32 v48, v4
	v_mov_b32_e32 v49, v4
	v_mov_b32_e32 v50, v4
	v_mov_b32_e32 v51, v4
	v_mov_b32_e32 v60, v4
	v_mov_b32_e32 v61, v4
	v_mov_b32_e32 v62, v4
	v_mov_b32_e32 v63, v4
	v_mov_b32_e32 v64, v4
	v_mov_b32_e32 v65, v4
	v_mov_b32_e32 v66, v4
	v_mov_b32_e32 v67, v4
	v_mov_b32_e32 v68, v4
	v_mov_b32_e32 v69, v4
	v_mov_b32_e32 v70, v4
	v_mov_b32_e32 v71, v4
	v_mov_b32_e32 v72, v4
	v_mov_b32_e32 v73, v4
	v_mov_b32_e32 v74, v4
	v_mov_b32_e32 v75, v4
	v_mov_b32_e32 v84, v4
	v_mov_b32_e32 v85, v4
	v_mov_b32_e32 v86, v4
	v_mov_b32_e32 v87, v4
	v_mov_b32_e32 v88, v4
	v_mov_b32_e32 v89, v4
	v_mov_b32_e32 v90, v4
	v_mov_b32_e32 v91, v4
	v_mov_b32_e32 v100, v4
	v_mov_b32_e32 v101, v4
	v_mov_b32_e32 v102, v4
	v_mov_b32_e32 v103, v4
	v_mov_b32_e32 v104, v4
	v_mov_b32_e32 v105, v4
	v_mov_b32_e32 v106, v4
	v_mov_b32_e32 v107, v4
	v_mov_b32_e32 v116, v4
	v_mov_b32_e32 v117, v4
	v_mov_b32_e32 v118, v4
	v_mov_b32_e32 v119, v4
	v_mov_b32_e32 v120, v4
	v_mov_b32_e32 v121, v4
	v_mov_b32_e32 v122, v4
	v_mov_b32_e32 v123, v4
	v_mov_b32_e32 v76, v4
	v_mov_b32_e32 v77, v4
	v_mov_b32_e32 v78, v4
	v_mov_b32_e32 v79, v4
	v_mov_b32_e32 v80, v4
	v_mov_b32_e32 v81, v4
	v_mov_b32_e32 v82, v4
	v_mov_b32_e32 v83, v4
	v_mov_b32_e32 v92, v4
	v_mov_b32_e32 v93, v4
	v_mov_b32_e32 v94, v4
	v_mov_b32_e32 v95, v4
	v_mov_b32_e32 v96, v4
	v_mov_b32_e32 v97, v4
	v_mov_b32_e32 v98, v4
	v_mov_b32_e32 v99, v4
	v_mov_b32_e32 v108, v4
	v_mov_b32_e32 v109, v4
	v_mov_b32_e32 v110, v4
	v_mov_b32_e32 v111, v4
	v_mov_b32_e32 v112, v4
	v_mov_b32_e32 v113, v4
	v_mov_b32_e32 v114, v4
	v_mov_b32_e32 v115, v4
	v_mov_b32_e32 v124, v4
	v_mov_b32_e32 v125, v4
	v_mov_b32_e32 v126, v4
	v_mov_b32_e32 v127, v4
	v_mov_b32_e32 v128, v4
	v_mov_b32_e32 v129, v4
	v_mov_b32_e32 v130, v4
	v_mov_b32_e32 v131, v4
	v_readfirstlane_b32 s100, v0
	s_nop 0
	s_cmpk_ge_u32 s100, 0x100
	s_cbranch_scc0 .Lsp_366


.LBB0_445:
	s_ashr_i32 s37, s36, 31
	s_lshl_b64 s[16:17], s[36:37], 20
	s_add_u32 s40, s0, s16
	s_addc_u32 s41, s1, s17
	s_and_b64 s[16:17], s[38:39], exec
	s_cselect_b32 s37, s41, s45
	s_cselect_b32 s88, s40, s44
	s_ashr_i32 s27, s26, 31
	s_lshl_b64 s[16:17], s[26:27], 20
	s_add_u32 s42, s3, s16
	s_addc_u32 s43, s31, s17
	s_and_b64 s[16:17], s[38:39], exec
	s_cselect_b32 s27, s43, s29
	s_cselect_b32 s89, s42, s28
	s_add_u32 s44, s44, 0x80080
	s_addc_u32 s45, s45, 0
	s_add_u32 s91, s28, 0x100
	v_mov_b32_e32 v4, 0
	v_mov_b32_e32 v235, 0x42000000
	v_mov_b32_e32 v233, 0x400
	v_mov_b64_e32 v[240:241], 0x1080
	s_addc_u32 s96, s29, 0
	s_mov_b32 vcc_lo, -2
	v_mov_b32_e32 v5, v4
	v_mov_b32_e32 v6, v4
	v_mov_b32_e32 v7, v4
	v_mov_b32_e32 v8, v4
	v_mov_b32_e32 v9, v4
	v_mov_b32_e32 v10, v4
	v_mov_b32_e32 v11, v4
	v_mov_b32_e32 v20, v4
	v_mov_b32_e32 v21, v4
	v_mov_b32_e32 v22, v4
	v_mov_b32_e32 v23, v4
	v_mov_b32_e32 v24, v4
	v_mov_b32_e32 v25, v4
	s_waitcnt lgkmcnt(0)
	v_mov_b32_e32 v26, v4
	v_mov_b32_e32 v27, v4
	v_mov_b32_e32 v36, v4
	v_mov_b32_e32 v37, v4
	v_mov_b32_e32 v38, v4
	v_mov_b32_e32 v39, v4
	v_mov_b32_e32 v40, v4
	v_mov_b32_e32 v41, v4
	v_mov_b32_e32 v42, v4
	v_mov_b32_e32 v43, v4
	v_mov_b32_e32 v52, v4
	v_mov_b32_e32 v53, v4
	v_mov_b32_e32 v54, v4
	v_mov_b32_e32 v55, v4
	v_mov_b32_e32 v56, v4
	v_mov_b32_e32 v57, v4
	v_mov_b32_e32 v58, v4
	v_mov_b32_e32 v59, v4
	v_mov_b32_e32 v12, v4
	v_mov_b32_e32 v13, v4
	v_mov_b32_e32 v14, v4
	v_mov_b32_e32 v15, v4
	v_mov_b32_e32 v16, v4
	v_mov_b32_e32 v17, v4
	v_mov_b32_e32 v18, v4
	v_mov_b32_e32 v19, v4
	v_mov_b32_e32 v28, v4
	v_mov_b32_e32 v29, v4
	v_mov_b32_e32 v30, v4
	v_mov_b32_e32 v31, v4
	v_mov_b32_e32 v32, v4
	v_mov_b32_e32 v33, v4
	v_mov_b32_e32 v34, v4
	v_mov_b32_e32 v35, v4
	v_mov_b32_e32 v44, v4
	v_mov_b32_e32 v45, v4
	v_mov_b32_e32 v46, v4
	v_mov_b32_e32 v47, v4
	v_mov_b32_e32 v48, v4
	v_mov_b32_e32 v49, v4
	v_mov_b32_e32 v50, v4
	v_mov_b32_e32 v51, v4
	v_mov_b32_e32 v60, v4
	v_mov_b32_e32 v61, v4
	v_mov_b32_e32 v62, v4
	v_mov_b32_e32 v63, v4
	v_mov_b32_e32 v64, v4
	v_mov_b32_e32 v65, v4
	v_mov_b32_e32 v66, v4
	v_mov_b32_e32 v67, v4
	v_mov_b32_e32 v68, v4
	v_mov_b32_e32 v69, v4
	v_mov_b32_e32 v70, v4
	v_mov_b32_e32 v71, v4
	v_mov_b32_e32 v72, v4
	v_mov_b32_e32 v73, v4
	v_mov_b32_e32 v74, v4
	v_mov_b32_e32 v75, v4
	v_mov_b32_e32 v84, v4
	v_mov_b32_e32 v85, v4
	v_mov_b32_e32 v86, v4
	v_mov_b32_e32 v87, v4
	v_mov_b32_e32 v88, v4
	v_mov_b32_e32 v89, v4
	v_mov_b32_e32 v90, v4
	v_mov_b32_e32 v91, v4
	v_mov_b32_e32 v100, v4
	v_mov_b32_e32 v101, v4
	v_mov_b32_e32 v102, v4
	v_mov_b32_e32 v103, v4
	v_mov_b32_e32 v104, v4
	v_mov_b32_e32 v105, v4
	v_mov_b32_e32 v106, v4
	v_mov_b32_e32 v107, v4
	v_mov_b32_e32 v116, v4
	v_mov_b32_e32 v117, v4
	v_mov_b32_e32 v118, v4
	v_mov_b32_e32 v119, v4
	v_mov_b32_e32 v120, v4
	v_mov_b32_e32 v121, v4
	v_mov_b32_e32 v122, v4
	v_mov_b32_e32 v123, v4
	v_mov_b32_e32 v76, v4
	v_mov_b32_e32 v77, v4
	v_mov_b32_e32 v78, v4
	v_mov_b32_e32 v79, v4
	v_mov_b32_e32 v80, v4
	v_mov_b32_e32 v81, v4
	v_mov_b32_e32 v82, v4
	v_mov_b32_e32 v83, v4
	v_mov_b32_e32 v92, v4
	v_mov_b32_e32 v93, v4
	v_mov_b32_e32 v94, v4
	v_mov_b32_e32 v95, v4
	v_mov_b32_e32 v96, v4
	v_mov_b32_e32 v97, v4
	v_mov_b32_e32 v98, v4
	v_mov_b32_e32 v99, v4
	v_mov_b32_e32 v108, v4
	v_mov_b32_e32 v109, v4
	v_mov_b32_e32 v110, v4
	v_mov_b32_e32 v111, v4
	v_mov_b32_e32 v112, v4
	v_mov_b32_e32 v113, v4
	v_mov_b32_e32 v114, v4
	v_mov_b32_e32 v115, v4
	v_mov_b32_e32 v124, v4
	v_mov_b32_e32 v125, v4
	v_mov_b32_e32 v126, v4
	v_mov_b32_e32 v127, v4
	v_mov_b32_e32 v128, v4
	v_mov_b32_e32 v129, v4
	v_mov_b32_e32 v130, v4
	v_mov_b32_e32 v131, v4
	v_readfirstlane_b32 s100, v0
	s_nop 0
	s_cmpk_ge_u32 s100, 0x100
	s_cbranch_scc0 .Lsp_446


.LBB0_789:
	s_ashr_i32 s19, s18, 31
	s_lshl_b64 s[10:11], s[18:19], 20
	v_readlane_b32 s16, v252, 15
	s_add_u32 s50, s16, s10
	v_readlane_b32 s10, v252, 16
	s_addc_u32 s51, s10, s11
	s_and_b64 s[10:11], s[46:47], exec
	s_cselect_b32 s19, s51, s73
	s_cselect_b32 s31, s50, s72
	s_ashr_i32 s23, s22, 31
	s_lshl_b64 s[10:11], s[22:23], 20
	s_add_u32 s26, s36, s10
	s_addc_u32 s27, s37, s11
	s_and_b64 s[10:11], s[46:47], exec
	s_cselect_b32 s23, s27, s29
	s_cselect_b32 s33, s26, s28
	s_add_u32 vcc_lo, s72, 0x80080
	s_addc_u32 vcc_hi, s73, 0
	s_add_u32 s48, s28, 0x100
	v_mov_b32_e32 v4, 0
	s_addc_u32 s49, s29, 0
	s_mov_b32 s10, -2
	v_mov_b32_e32 v5, v4
	v_mov_b32_e32 v6, v4
	v_mov_b32_e32 v7, v4
	v_mov_b32_e32 v8, v4
	v_mov_b32_e32 v9, v4
	v_mov_b32_e32 v10, v4
	v_mov_b32_e32 v11, v4
	v_mov_b32_e32 v20, v4
	v_mov_b32_e32 v21, v4
	v_mov_b32_e32 v22, v4
	v_mov_b32_e32 v23, v4
	v_mov_b32_e32 v24, v4
	v_mov_b32_e32 v25, v4
	s_waitcnt lgkmcnt(0)
	v_mov_b32_e32 v26, v4
	v_mov_b32_e32 v27, v4
	v_mov_b32_e32 v36, v4
	v_mov_b32_e32 v37, v4
	v_mov_b32_e32 v38, v4
	v_mov_b32_e32 v39, v4
	v_mov_b32_e32 v40, v4
	v_mov_b32_e32 v41, v4
	v_mov_b32_e32 v42, v4
	v_mov_b32_e32 v43, v4
	v_mov_b32_e32 v52, v4
	v_mov_b32_e32 v53, v4
	v_mov_b32_e32 v54, v4
	v_mov_b32_e32 v55, v4
	v_mov_b32_e32 v56, v4
	v_mov_b32_e32 v57, v4
	v_mov_b32_e32 v58, v4
	v_mov_b32_e32 v59, v4
	v_mov_b32_e32 v12, v4
	v_mov_b32_e32 v13, v4
	v_mov_b32_e32 v14, v4
	v_mov_b32_e32 v15, v4
	v_mov_b32_e32 v16, v4
	v_mov_b32_e32 v17, v4
	v_mov_b32_e32 v18, v4
	v_mov_b32_e32 v19, v4
	v_mov_b32_e32 v28, v4
	v_mov_b32_e32 v29, v4
	v_mov_b32_e32 v30, v4
	v_mov_b32_e32 v31, v4
	v_mov_b32_e32 v32, v4
	v_mov_b32_e32 v33, v4
	v_mov_b32_e32 v34, v4
	v_mov_b32_e32 v35, v4
	v_mov_b32_e32 v44, v4
	v_mov_b32_e32 v45, v4
	v_mov_b32_e32 v46, v4
	v_mov_b32_e32 v47, v4
	v_mov_b32_e32 v48, v4
	v_mov_b32_e32 v49, v4
	v_mov_b32_e32 v50, v4
	v_mov_b32_e32 v51, v4
	v_mov_b32_e32 v60, v4
	v_mov_b32_e32 v61, v4
	v_mov_b32_e32 v62, v4
	v_mov_b32_e32 v63, v4
	v_mov_b32_e32 v64, v4
	v_mov_b32_e32 v65, v4
	v_mov_b32_e32 v66, v4
	v_mov_b32_e32 v67, v4
	v_mov_b32_e32 v68, v4
	v_mov_b32_e32 v69, v4
	v_mov_b32_e32 v70, v4
	v_mov_b32_e32 v71, v4
	v_mov_b32_e32 v72, v4
	v_mov_b32_e32 v73, v4
	v_mov_b32_e32 v74, v4
	v_mov_b32_e32 v75, v4
	v_mov_b32_e32 v84, v4
	v_mov_b32_e32 v85, v4
	v_mov_b32_e32 v86, v4
	v_mov_b32_e32 v87, v4
	v_mov_b32_e32 v88, v4
	v_mov_b32_e32 v89, v4
	v_mov_b32_e32 v90, v4
	v_mov_b32_e32 v91, v4
	v_mov_b32_e32 v100, v4
	v_mov_b32_e32 v101, v4
	v_mov_b32_e32 v102, v4
	v_mov_b32_e32 v103, v4
	v_mov_b32_e32 v104, v4
	v_mov_b32_e32 v105, v4
	v_mov_b32_e32 v106, v4
	v_mov_b32_e32 v107, v4
	v_mov_b32_e32 v116, v4
	v_mov_b32_e32 v117, v4
	v_mov_b32_e32 v118, v4
	v_mov_b32_e32 v119, v4
	v_mov_b32_e32 v120, v4
	v_mov_b32_e32 v121, v4
	v_mov_b32_e32 v122, v4
	v_mov_b32_e32 v123, v4
	v_mov_b32_e32 v76, v4
	v_mov_b32_e32 v77, v4
	v_mov_b32_e32 v78, v4
	v_mov_b32_e32 v79, v4
	v_mov_b32_e32 v80, v4
	v_mov_b32_e32 v81, v4
	v_mov_b32_e32 v82, v4
	v_mov_b32_e32 v83, v4
	v_mov_b32_e32 v92, v4
	v_mov_b32_e32 v93, v4
	v_mov_b32_e32 v94, v4
	v_mov_b32_e32 v95, v4
	v_mov_b32_e32 v96, v4
	v_mov_b32_e32 v97, v4
	v_mov_b32_e32 v98, v4
	v_mov_b32_e32 v99, v4
	v_mov_b32_e32 v108, v4
	v_mov_b32_e32 v109, v4
	v_mov_b32_e32 v110, v4
	v_mov_b32_e32 v111, v4
	v_mov_b32_e32 v112, v4
	v_mov_b32_e32 v113, v4
	v_mov_b32_e32 v114, v4
	v_mov_b32_e32 v115, v4
	v_mov_b32_e32 v124, v4
	v_mov_b32_e32 v125, v4
	v_mov_b32_e32 v126, v4
	v_mov_b32_e32 v127, v4
	v_mov_b32_e32 v128, v4
	v_mov_b32_e32 v129, v4
	v_mov_b32_e32 v130, v4
	v_mov_b32_e32 v131, v4
	v_readfirstlane_b32 s100, v0
	s_nop 0
	s_cmpk_ge_u32 s100, 0x100
	s_cbranch_scc0 .Lsp_790


.LBB0_869:
	s_ashr_i32 s37, s36, 31
	s_lshl_b64 s[16:17], s[36:37], 20
	s_add_u32 s40, s0, s16
	s_addc_u32 s41, s1, s17
	s_and_b64 s[16:17], s[38:39], exec
	s_cselect_b32 s37, s41, s45
	s_cselect_b32 s88, s40, s44
	s_ashr_i32 s27, s26, 31
	s_lshl_b64 s[16:17], s[26:27], 20
	s_add_u32 s42, s3, s16
	s_addc_u32 s43, s31, s17
	s_and_b64 s[16:17], s[38:39], exec
	s_cselect_b32 s27, s43, s29
	s_cselect_b32 s89, s42, s28
	s_add_u32 s44, s44, 0x80080
	s_addc_u32 s45, s45, 0
	s_add_u32 s91, s28, 0x100
	v_mov_b32_e32 v4, 0
	s_addc_u32 s96, s29, 0
	s_mov_b32 vcc_lo, -2
	v_mov_b32_e32 v5, v4
	v_mov_b32_e32 v6, v4
	v_mov_b32_e32 v7, v4
	v_mov_b32_e32 v8, v4
	v_mov_b32_e32 v9, v4
	v_mov_b32_e32 v10, v4
	v_mov_b32_e32 v11, v4
	v_mov_b32_e32 v20, v4
	v_mov_b32_e32 v21, v4
	v_mov_b32_e32 v22, v4
	v_mov_b32_e32 v23, v4
	v_mov_b32_e32 v24, v4
	v_mov_b32_e32 v25, v4
	s_waitcnt lgkmcnt(0)
	v_mov_b32_e32 v26, v4
	v_mov_b32_e32 v27, v4
	v_mov_b32_e32 v36, v4
	v_mov_b32_e32 v37, v4
	v_mov_b32_e32 v38, v4
	v_mov_b32_e32 v39, v4
	v_mov_b32_e32 v40, v4
	v_mov_b32_e32 v41, v4
	v_mov_b32_e32 v42, v4
	v_mov_b32_e32 v43, v4
	v_mov_b32_e32 v52, v4
	v_mov_b32_e32 v53, v4
	v_mov_b32_e32 v54, v4
	v_mov_b32_e32 v55, v4
	v_mov_b32_e32 v56, v4
	v_mov_b32_e32 v57, v4
	v_mov_b32_e32 v58, v4
	v_mov_b32_e32 v59, v4
	v_mov_b32_e32 v12, v4
	v_mov_b32_e32 v13, v4
	v_mov_b32_e32 v14, v4
	v_mov_b32_e32 v15, v4
	v_mov_b32_e32 v16, v4
	v_mov_b32_e32 v17, v4
	v_mov_b32_e32 v18, v4
	v_mov_b32_e32 v19, v4
	v_mov_b32_e32 v28, v4
	v_mov_b32_e32 v29, v4
	v_mov_b32_e32 v30, v4
	v_mov_b32_e32 v31, v4
	v_mov_b32_e32 v32, v4
	v_mov_b32_e32 v33, v4
	v_mov_b32_e32 v34, v4
	v_mov_b32_e32 v35, v4
	v_mov_b32_e32 v44, v4
	v_mov_b32_e32 v45, v4
	v_mov_b32_e32 v46, v4
	v_mov_b32_e32 v47, v4
	v_mov_b32_e32 v48, v4
	v_mov_b32_e32 v49, v4
	v_mov_b32_e32 v50, v4
	v_mov_b32_e32 v51, v4
	v_mov_b32_e32 v60, v4
	v_mov_b32_e32 v61, v4
	v_mov_b32_e32 v62, v4
	v_mov_b32_e32 v63, v4
	v_mov_b32_e32 v64, v4
	v_mov_b32_e32 v65, v4
	v_mov_b32_e32 v66, v4
	v_mov_b32_e32 v67, v4
	v_mov_b32_e32 v68, v4
	v_mov_b32_e32 v69, v4
	v_mov_b32_e32 v70, v4
	v_mov_b32_e32 v71, v4
	v_mov_b32_e32 v72, v4
	v_mov_b32_e32 v73, v4
	v_mov_b32_e32 v74, v4
	v_mov_b32_e32 v75, v4
	v_mov_b32_e32 v84, v4
	v_mov_b32_e32 v85, v4
	v_mov_b32_e32 v86, v4
	v_mov_b32_e32 v87, v4
	v_mov_b32_e32 v88, v4
	v_mov_b32_e32 v89, v4
	v_mov_b32_e32 v90, v4
	v_mov_b32_e32 v91, v4
	v_mov_b32_e32 v100, v4
	v_mov_b32_e32 v101, v4
	v_mov_b32_e32 v102, v4
	v_mov_b32_e32 v103, v4
	v_mov_b32_e32 v104, v4
	v_mov_b32_e32 v105, v4
	v_mov_b32_e32 v106, v4
	v_mov_b32_e32 v107, v4
	v_mov_b32_e32 v116, v4
	v_mov_b32_e32 v117, v4
	v_mov_b32_e32 v118, v4
	v_mov_b32_e32 v119, v4
	v_mov_b32_e32 v120, v4
	v_mov_b32_e32 v121, v4
	v_mov_b32_e32 v122, v4
	v_mov_b32_e32 v123, v4
	v_mov_b32_e32 v76, v4
	v_mov_b32_e32 v77, v4
	v_mov_b32_e32 v78, v4
	v_mov_b32_e32 v79, v4
	v_mov_b32_e32 v80, v4
	v_mov_b32_e32 v81, v4
	v_mov_b32_e32 v82, v4
	v_mov_b32_e32 v83, v4
	v_mov_b32_e32 v92, v4
	v_mov_b32_e32 v93, v4
	v_mov_b32_e32 v94, v4
	v_mov_b32_e32 v95, v4
	v_mov_b32_e32 v96, v4
	v_mov_b32_e32 v97, v4
	v_mov_b32_e32 v98, v4
	v_mov_b32_e32 v99, v4
	v_mov_b32_e32 v108, v4
	v_mov_b32_e32 v109, v4
	v_mov_b32_e32 v110, v4
	v_mov_b32_e32 v111, v4
	v_mov_b32_e32 v112, v4
	v_mov_b32_e32 v113, v4
	v_mov_b32_e32 v114, v4
	v_mov_b32_e32 v115, v4
	v_mov_b32_e32 v124, v4
	v_mov_b32_e32 v125, v4
	v_mov_b32_e32 v126, v4
	v_mov_b32_e32 v127, v4
	v_mov_b32_e32 v128, v4
	v_mov_b32_e32 v129, v4
	v_mov_b32_e32 v130, v4
	v_mov_b32_e32 v131, v4
	v_readfirstlane_b32 s100, v0
	s_nop 0
	s_cmpk_ge_u32 s100, 0x100
	s_cbranch_scc0 .Lsp_870


.LBB0_1034:
	s_add_u32 vcc_lo, s28, 0x100
	v_mov_b32_e32 v4, 0
	s_addc_u32 vcc_hi, s29, 0
	s_mov_b32 s48, -2
	v_mov_b32_e32 v5, v4
	v_mov_b32_e32 v6, v4
	v_mov_b32_e32 v7, v4
	v_mov_b32_e32 v8, v4
	v_mov_b32_e32 v9, v4
	v_mov_b32_e32 v10, v4
	v_mov_b32_e32 v11, v4
	v_mov_b32_e32 v20, v4
	v_mov_b32_e32 v21, v4
	v_mov_b32_e32 v22, v4
	v_mov_b32_e32 v23, v4
	v_mov_b32_e32 v24, v4
	v_mov_b32_e32 v25, v4
	s_waitcnt lgkmcnt(0)
	v_mov_b32_e32 v26, v4
	v_mov_b32_e32 v27, v4
	v_mov_b32_e32 v36, v4
	v_mov_b32_e32 v37, v4
	v_mov_b32_e32 v38, v4
	v_mov_b32_e32 v39, v4
	v_mov_b32_e32 v40, v4
	v_mov_b32_e32 v41, v4
	v_mov_b32_e32 v42, v4
	v_mov_b32_e32 v43, v4
	v_mov_b32_e32 v52, v4
	v_mov_b32_e32 v53, v4
	v_mov_b32_e32 v54, v4
	v_mov_b32_e32 v55, v4
	v_mov_b32_e32 v56, v4
	v_mov_b32_e32 v57, v4
	v_mov_b32_e32 v58, v4
	v_mov_b32_e32 v59, v4
	v_mov_b32_e32 v12, v4
	v_mov_b32_e32 v13, v4
	v_mov_b32_e32 v14, v4
	v_mov_b32_e32 v15, v4
	v_mov_b32_e32 v16, v4
	v_mov_b32_e32 v17, v4
	v_mov_b32_e32 v18, v4
	v_mov_b32_e32 v19, v4
	v_mov_b32_e32 v28, v4
	v_mov_b32_e32 v29, v4
	v_mov_b32_e32 v30, v4
	v_mov_b32_e32 v31, v4
	v_mov_b32_e32 v32, v4
	v_mov_b32_e32 v33, v4
	v_mov_b32_e32 v34, v4
	v_mov_b32_e32 v35, v4
	v_mov_b32_e32 v44, v4
	v_mov_b32_e32 v45, v4
	v_mov_b32_e32 v46, v4
	v_mov_b32_e32 v47, v4
	v_mov_b32_e32 v48, v4
	v_mov_b32_e32 v49, v4
	v_mov_b32_e32 v50, v4
	v_mov_b32_e32 v51, v4
	v_mov_b32_e32 v60, v4
	v_mov_b32_e32 v61, v4
	v_mov_b32_e32 v62, v4
	v_mov_b32_e32 v63, v4
	v_mov_b32_e32 v64, v4
	v_mov_b32_e32 v65, v4
	v_mov_b32_e32 v66, v4
	v_mov_b32_e32 v67, v4
	v_mov_b32_e32 v68, v4
	v_mov_b32_e32 v69, v4
	v_mov_b32_e32 v70, v4
	v_mov_b32_e32 v71, v4
	v_mov_b32_e32 v72, v4
	v_mov_b32_e32 v73, v4
	v_mov_b32_e32 v74, v4
	v_mov_b32_e32 v75, v4
	v_mov_b32_e32 v84, v4
	v_mov_b32_e32 v85, v4
	v_mov_b32_e32 v86, v4
	v_mov_b32_e32 v87, v4
	v_mov_b32_e32 v88, v4
	v_mov_b32_e32 v89, v4
	v_mov_b32_e32 v90, v4
	v_mov_b32_e32 v91, v4
	v_mov_b32_e32 v100, v4
	v_mov_b32_e32 v101, v4
	v_mov_b32_e32 v102, v4
	v_mov_b32_e32 v103, v4
	v_mov_b32_e32 v104, v4
	v_mov_b32_e32 v105, v4
	v_mov_b32_e32 v106, v4
	v_mov_b32_e32 v107, v4
	v_mov_b32_e32 v116, v4
	v_mov_b32_e32 v117, v4
	v_mov_b32_e32 v118, v4
	v_mov_b32_e32 v119, v4
	v_mov_b32_e32 v120, v4
	v_mov_b32_e32 v121, v4
	v_mov_b32_e32 v122, v4
	v_mov_b32_e32 v123, v4
	v_mov_b32_e32 v76, v4
	v_mov_b32_e32 v77, v4
	v_mov_b32_e32 v78, v4
	v_mov_b32_e32 v79, v4
	v_mov_b32_e32 v80, v4
	v_mov_b32_e32 v81, v4
	v_mov_b32_e32 v82, v4
	v_mov_b32_e32 v83, v4
	v_mov_b32_e32 v92, v4
	v_mov_b32_e32 v93, v4
	v_mov_b32_e32 v94, v4
	v_mov_b32_e32 v95, v4
	v_mov_b32_e32 v96, v4
	v_mov_b32_e32 v97, v4
	v_mov_b32_e32 v98, v4
	v_mov_b32_e32 v99, v4
	v_mov_b32_e32 v108, v4
	v_mov_b32_e32 v109, v4
	v_mov_b32_e32 v110, v4
	v_mov_b32_e32 v111, v4
	v_mov_b32_e32 v112, v4
	v_mov_b32_e32 v113, v4
	v_mov_b32_e32 v114, v4
	v_mov_b32_e32 v115, v4
	v_mov_b32_e32 v124, v4
	v_mov_b32_e32 v125, v4
	v_mov_b32_e32 v126, v4
	v_mov_b32_e32 v127, v4
	v_mov_b32_e32 v128, v4
	v_mov_b32_e32 v129, v4
	v_mov_b32_e32 v130, v4
	v_mov_b32_e32 v131, v4
	v_readfirstlane_b32 s100, v0
	s_nop 0
	s_cmpk_ge_u32 s100, 0x100
	s_cbranch_scc0 .Lsp_1035

